# layer 2 input projection: 80 indexer-key/weight columns by a thin MFMA routine per workgroup, tiled GEMM 16 column tiles = exactly 5 rounds (layer 0 unchanged)
# baseline (speedup 1.0000x reference)
; DI void run_phase(const Params& p, int ph, char* smem) {
;     ...
;       GemmP g1 = mk_gemm(XB, DM, (const u16*)(ws + (even ? O_EVIN + j * SZ_EVIN : O_ODIN + j * SZ_ODIN)), DM, DM, 64, even ? EV_N / 256 : OD_N / 256);
;       g1.Cb = (u16*)(ws + O_H); g1.ldc = HLD; g1.aux = (float*)(ws + O_AUX);
;       if (even) { g1.aux_n0 = 4160; g1.aux_cnt = 16; g1.aux_scale = 0.25f; } else { g1.aux_n0 = 5120; g1.aux_cnt = 8; g1.aux_scale = 1.f; }
.LBB0_982:
	s_andn2_b64 vcc, exec, s[6:7]
	s_cbranch_vccnz .LBB0_985
	s_mov_b32 s8, 17
	s_cmp_eq_u32 s12, 0
	s_cbranch_scc1 .Lki_skip
	v_lshrrev_b32_e32 v2, 6, v201
	v_and_b32_e32 v3, 15, v201
	v_bfe_u32 v4, v201, 4, 2
	v_readlane_b32 s14, v254, 0
	v_readfirstlane_b32 s15, v2
	s_lshl_b32 s14, s14, 6
	s_and_b32 s22, s15, 3
	s_lshr_b32 s15, s15, 2
	s_lshl_b32 s22, s22, 4
	s_add_i32 s14, s14, s22
	v_add_u32_e32 v5, s14, v3
	v_lshlrev_b32_e32 v6, 4, v4
	v_lshl_or_b32 v8, v5, 12, v6
	s_mul_i32 s22, s15, 48
	v_add_u32_e32 v9, s22, v3
	v_lshl_or_b32 v9, v9, 12, v6
	v_add_u32_e32 v10, 0x10000, v9
	s_sub_i32 s22, 1, s15
	s_lshl_b32 s22, s22, 16
	v_add_u32_e32 v11, s22, v10
	s_add_u32 s16, s90, 0x1a500000
	s_addc_u32 s17, s91, 0
	s_mul_i32 s22, s58, 0x1100000
	s_mul_hi_i32 s23, s58, 0x1100000
	s_add_u32 s18, s90, s22
	s_addc_u32 s19, s91, s23
	s_add_u32 s18, s18, 0x1000000
	s_addc_u32 s19, s19, 0
	s_add_u32 s20, s90, 0x39300000
	s_addc_u32 s21, s91, 0
	v_mov_b32_e32 v176, 0
	v_mov_b32_e32 v177, 0
	v_mov_b32_e32 v178, 0
	v_mov_b32_e32 v179, 0
	v_mov_b32_e32 v180, 0
	v_mov_b32_e32 v181, 0
	v_mov_b32_e32 v182, 0
	v_mov_b32_e32 v183, 0
	v_mov_b32_e32 v184, 0
	v_mov_b32_e32 v185, 0
	v_mov_b32_e32 v186, 0
	v_mov_b32_e32 v187, 0
	global_load_dwordx4 v[16:19], v8, s[16:17]
	global_load_dwordx4 v[20:23], v9, s[18:19]
	global_load_dwordx4 v[24:27], v10, s[18:19]
	global_load_dwordx4 v[28:31], v11, s[18:19]
	global_load_dwordx4 v[32:35], v8, s[16:17] offset:64
	global_load_dwordx4 v[36:39], v9, s[18:19] offset:64
	global_load_dwordx4 v[40:43], v10, s[18:19] offset:64
	global_load_dwordx4 v[44:47], v11, s[18:19] offset:64
	global_load_dwordx4 v[48:51], v8, s[16:17] offset:128
	global_load_dwordx4 v[52:55], v9, s[18:19] offset:128
	global_load_dwordx4 v[56:59], v10, s[18:19] offset:128
	global_load_dwordx4 v[60:63], v11, s[18:19] offset:128
	global_load_dwordx4 v[64:67], v8, s[16:17] offset:192
	global_load_dwordx4 v[68:71], v9, s[18:19] offset:192
	global_load_dwordx4 v[72:75], v10, s[18:19] offset:192
	global_load_dwordx4 v[76:79], v11, s[18:19] offset:192
	global_load_dwordx4 v[80:83], v8, s[16:17] offset:256
	global_load_dwordx4 v[84:87], v9, s[18:19] offset:256
	global_load_dwordx4 v[88:91], v10, s[18:19] offset:256
	global_load_dwordx4 v[92:95], v11, s[18:19] offset:256
	global_load_dwordx4 v[96:99], v8, s[16:17] offset:320
	global_load_dwordx4 v[100:103], v9, s[18:19] offset:320
	global_load_dwordx4 v[104:107], v10, s[18:19] offset:320
	global_load_dwordx4 v[108:111], v11, s[18:19] offset:320
	global_load_dwordx4 v[112:115], v8, s[16:17] offset:384
	global_load_dwordx4 v[116:119], v9, s[18:19] offset:384
	global_load_dwordx4 v[120:123], v10, s[18:19] offset:384
	global_load_dwordx4 v[124:127], v11, s[18:19] offset:384
	global_load_dwordx4 v[128:131], v8, s[16:17] offset:448
	global_load_dwordx4 v[132:135], v9, s[18:19] offset:448
	global_load_dwordx4 v[136:139], v10, s[18:19] offset:448
	global_load_dwordx4 v[140:143], v11, s[18:19] offset:448
	global_load_dwordx4 v[144:147], v8, s[16:17] offset:512
	global_load_dwordx4 v[148:151], v9, s[18:19] offset:512
	global_load_dwordx4 v[152:155], v10, s[18:19] offset:512
	global_load_dwordx4 v[156:159], v11, s[18:19] offset:512
	global_load_dwordx4 v[160:163], v8, s[16:17] offset:576
	global_load_dwordx4 v[164:167], v9, s[18:19] offset:576
	global_load_dwordx4 v[168:171], v10, s[18:19] offset:576
	global_load_dwordx4 v[172:175], v11, s[18:19] offset:576
	s_waitcnt vmcnt(32)
	v_mfma_f32_16x16x32_bf16 v[176:179], v[20:23], v[16:19], v[176:179]
	v_mfma_f32_16x16x32_bf16 v[180:183], v[24:27], v[16:19], v[180:183]
	v_mfma_f32_16x16x32_bf16 v[184:187], v[28:31], v[16:19], v[184:187]
	v_mfma_f32_16x16x32_bf16 v[176:179], v[36:39], v[32:35], v[176:179]
	v_mfma_f32_16x16x32_bf16 v[180:183], v[40:43], v[32:35], v[180:183]
	v_mfma_f32_16x16x32_bf16 v[184:187], v[44:47], v[32:35], v[184:187]
	global_load_dwordx4 v[16:19], v8, s[16:17] offset:640
	global_load_dwordx4 v[20:23], v9, s[18:19] offset:640
	global_load_dwordx4 v[24:27], v10, s[18:19] offset:640
	global_load_dwordx4 v[28:31], v11, s[18:19] offset:640
	global_load_dwordx4 v[32:35], v8, s[16:17] offset:704
	global_load_dwordx4 v[36:39], v9, s[18:19] offset:704
	global_load_dwordx4 v[40:43], v10, s[18:19] offset:704
	global_load_dwordx4 v[44:47], v11, s[18:19] offset:704
	s_waitcnt vmcnt(32)
	v_mfma_f32_16x16x32_bf16 v[176:179], v[52:55], v[48:51], v[176:179]
	v_mfma_f32_16x16x32_bf16 v[180:183], v[56:59], v[48:51], v[180:183]
	v_mfma_f32_16x16x32_bf16 v[184:187], v[60:63], v[48:51], v[184:187]
	v_mfma_f32_16x16x32_bf16 v[176:179], v[68:71], v[64:67], v[176:179]
	v_mfma_f32_16x16x32_bf16 v[180:183], v[72:75], v[64:67], v[180:183]
	v_mfma_f32_16x16x32_bf16 v[184:187], v[76:79], v[64:67], v[184:187]
	global_load_dwordx4 v[48:51], v8, s[16:17] offset:768
	global_load_dwordx4 v[52:55], v9, s[18:19] offset:768
	global_load_dwordx4 v[56:59], v10, s[18:19] offset:768
	global_load_dwordx4 v[60:63], v11, s[18:19] offset:768
	global_load_dwordx4 v[64:67], v8, s[16:17] offset:832
	global_load_dwordx4 v[68:71], v9, s[18:19] offset:832
	global_load_dwordx4 v[72:75], v10, s[18:19] offset:832
	global_load_dwordx4 v[76:79], v11, s[18:19] offset:832
	s_waitcnt vmcnt(32)
	v_mfma_f32_16x16x32_bf16 v[176:179], v[84:87], v[80:83], v[176:179]
	v_mfma_f32_16x16x32_bf16 v[180:183], v[88:91], v[80:83], v[180:183]
	v_mfma_f32_16x16x32_bf16 v[184:187], v[92:95], v[80:83], v[184:187]
	v_mfma_f32_16x16x32_bf16 v[176:179], v[100:103], v[96:99], v[176:179]
	v_mfma_f32_16x16x32_bf16 v[180:183], v[104:107], v[96:99], v[180:183]
	v_mfma_f32_16x16x32_bf16 v[184:187], v[108:111], v[96:99], v[184:187]
	global_load_dwordx4 v[80:83], v8, s[16:17] offset:896
	global_load_dwordx4 v[84:87], v9, s[18:19] offset:896
	global_load_dwordx4 v[88:91], v10, s[18:19] offset:896
	global_load_dwordx4 v[92:95], v11, s[18:19] offset:896
	global_load_dwordx4 v[96:99], v8, s[16:17] offset:960
	global_load_dwordx4 v[100:103], v9, s[18:19] offset:960
	global_load_dwordx4 v[104:107], v10, s[18:19] offset:960
	global_load_dwordx4 v[108:111], v11, s[18:19] offset:960
	s_waitcnt vmcnt(32)
	v_mfma_f32_16x16x32_bf16 v[176:179], v[116:119], v[112:115], v[176:179]
	v_mfma_f32_16x16x32_bf16 v[180:183], v[120:123], v[112:115], v[180:183]
	v_mfma_f32_16x16x32_bf16 v[184:187], v[124:127], v[112:115], v[184:187]
	v_mfma_f32_16x16x32_bf16 v[176:179], v[132:135], v[128:131], v[176:179]
	v_mfma_f32_16x16x32_bf16 v[180:183], v[136:139], v[128:131], v[180:183]
	v_mfma_f32_16x16x32_bf16 v[184:187], v[140:143], v[128:131], v[184:187]
	global_load_dwordx4 v[112:115], v8, s[16:17] offset:1024
	global_load_dwordx4 v[116:119], v9, s[18:19] offset:1024
	global_load_dwordx4 v[120:123], v10, s[18:19] offset:1024
	global_load_dwordx4 v[124:127], v11, s[18:19] offset:1024
	global_load_dwordx4 v[128:131], v8, s[16:17] offset:1088
	global_load_dwordx4 v[132:135], v9, s[18:19] offset:1088
	global_load_dwordx4 v[136:139], v10, s[18:19] offset:1088
	global_load_dwordx4 v[140:143], v11, s[18:19] offset:1088
	s_waitcnt vmcnt(32)
	v_mfma_f32_16x16x32_bf16 v[176:179], v[148:151], v[144:147], v[176:179]
	v_mfma_f32_16x16x32_bf16 v[180:183], v[152:155], v[144:147], v[180:183]
	v_mfma_f32_16x16x32_bf16 v[184:187], v[156:159], v[144:147], v[184:187]
	v_mfma_f32_16x16x32_bf16 v[176:179], v[164:167], v[160:163], v[176:179]
	v_mfma_f32_16x16x32_bf16 v[180:183], v[168:171], v[160:163], v[180:183]
	v_mfma_f32_16x16x32_bf16 v[184:187], v[172:175], v[160:163], v[184:187]
	global_load_dwordx4 v[144:147], v8, s[16:17] offset:1152
	global_load_dwordx4 v[148:151], v9, s[18:19] offset:1152
	global_load_dwordx4 v[152:155], v10, s[18:19] offset:1152
	global_load_dwordx4 v[156:159], v11, s[18:19] offset:1152
	global_load_dwordx4 v[160:163], v8, s[16:17] offset:1216
	global_load_dwordx4 v[164:167], v9, s[18:19] offset:1216
	global_load_dwordx4 v[168:171], v10, s[18:19] offset:1216
	global_load_dwordx4 v[172:175], v11, s[18:19] offset:1216
	s_waitcnt vmcnt(32)
	v_mfma_f32_16x16x32_bf16 v[176:179], v[20:23], v[16:19], v[176:179]
	v_mfma_f32_16x16x32_bf16 v[180:183], v[24:27], v[16:19], v[180:183]
	v_mfma_f32_16x16x32_bf16 v[184:187], v[28:31], v[16:19], v[184:187]
	v_mfma_f32_16x16x32_bf16 v[176:179], v[36:39], v[32:35], v[176:179]
	v_mfma_f32_16x16x32_bf16 v[180:183], v[40:43], v[32:35], v[180:183]
	v_mfma_f32_16x16x32_bf16 v[184:187], v[44:47], v[32:35], v[184:187]
	global_load_dwordx4 v[16:19], v8, s[16:17] offset:1280
	global_load_dwordx4 v[20:23], v9, s[18:19] offset:1280
	global_load_dwordx4 v[24:27], v10, s[18:19] offset:1280
	global_load_dwordx4 v[28:31], v11, s[18:19] offset:1280
	global_load_dwordx4 v[32:35], v8, s[16:17] offset:1344
	global_load_dwordx4 v[36:39], v9, s[18:19] offset:1344
	global_load_dwordx4 v[40:43], v10, s[18:19] offset:1344
	global_load_dwordx4 v[44:47], v11, s[18:19] offset:1344
	s_waitcnt vmcnt(32)
	v_mfma_f32_16x16x32_bf16 v[176:179], v[52:55], v[48:51], v[176:179]
	v_mfma_f32_16x16x32_bf16 v[180:183], v[56:59], v[48:51], v[180:183]
	v_mfma_f32_16x16x32_bf16 v[184:187], v[60:63], v[48:51], v[184:187]
	v_mfma_f32_16x16x32_bf16 v[176:179], v[68:71], v[64:67], v[176:179]
	v_mfma_f32_16x16x32_bf16 v[180:183], v[72:75], v[64:67], v[180:183]
	v_mfma_f32_16x16x32_bf16 v[184:187], v[76:79], v[64:67], v[184:187]
	global_load_dwordx4 v[48:51], v8, s[16:17] offset:1408
	global_load_dwordx4 v[52:55], v9, s[18:19] offset:1408
	global_load_dwordx4 v[56:59], v10, s[18:19] offset:1408
	global_load_dwordx4 v[60:63], v11, s[18:19] offset:1408
	global_load_dwordx4 v[64:67], v8, s[16:17] offset:1472
	global_load_dwordx4 v[68:71], v9, s[18:19] offset:1472
	global_load_dwordx4 v[72:75], v10, s[18:19] offset:1472
	global_load_dwordx4 v[76:79], v11, s[18:19] offset:1472
	s_waitcnt vmcnt(32)
	v_mfma_f32_16x16x32_bf16 v[176:179], v[84:87], v[80:83], v[176:179]
	v_mfma_f32_16x16x32_bf16 v[180:183], v[88:91], v[80:83], v[180:183]
	v_mfma_f32_16x16x32_bf16 v[184:187], v[92:95], v[80:83], v[184:187]
	v_mfma_f32_16x16x32_bf16 v[176:179], v[100:103], v[96:99], v[176:179]
	v_mfma_f32_16x16x32_bf16 v[180:183], v[104:107], v[96:99], v[180:183]
	v_mfma_f32_16x16x32_bf16 v[184:187], v[108:111], v[96:99], v[184:187]
	global_load_dwordx4 v[80:83], v8, s[16:17] offset:1536
	global_load_dwordx4 v[84:87], v9, s[18:19] offset:1536
	global_load_dwordx4 v[88:91], v10, s[18:19] offset:1536
	global_load_dwordx4 v[92:95], v11, s[18:19] offset:1536
	global_load_dwordx4 v[96:99], v8, s[16:17] offset:1600
	global_load_dwordx4 v[100:103], v9, s[18:19] offset:1600
	global_load_dwordx4 v[104:107], v10, s[18:19] offset:1600
	global_load_dwordx4 v[108:111], v11, s[18:19] offset:1600
	s_waitcnt vmcnt(32)
	v_mfma_f32_16x16x32_bf16 v[176:179], v[116:119], v[112:115], v[176:179]
	v_mfma_f32_16x16x32_bf16 v[180:183], v[120:123], v[112:115], v[180:183]
	v_mfma_f32_16x16x32_bf16 v[184:187], v[124:127], v[112:115], v[184:187]
	v_mfma_f32_16x16x32_bf16 v[176:179], v[132:135], v[128:131], v[176:179]
	v_mfma_f32_16x16x32_bf16 v[180:183], v[136:139], v[128:131], v[180:183]
	v_mfma_f32_16x16x32_bf16 v[184:187], v[140:143], v[128:131], v[184:187]
	global_load_dwordx4 v[112:115], v8, s[16:17] offset:1664
	global_load_dwordx4 v[116:119], v9, s[18:19] offset:1664
	global_load_dwordx4 v[120:123], v10, s[18:19] offset:1664
	global_load_dwordx4 v[124:127], v11, s[18:19] offset:1664
	global_load_dwordx4 v[128:131], v8, s[16:17] offset:1728
	global_load_dwordx4 v[132:135], v9, s[18:19] offset:1728
	global_load_dwordx4 v[136:139], v10, s[18:19] offset:1728
	global_load_dwordx4 v[140:143], v11, s[18:19] offset:1728
	s_waitcnt vmcnt(32)
	v_mfma_f32_16x16x32_bf16 v[176:179], v[148:151], v[144:147], v[176:179]
	v_mfma_f32_16x16x32_bf16 v[180:183], v[152:155], v[144:147], v[180:183]
	v_mfma_f32_16x16x32_bf16 v[184:187], v[156:159], v[144:147], v[184:187]
	v_mfma_f32_16x16x32_bf16 v[176:179], v[164:167], v[160:163], v[176:179]
	v_mfma_f32_16x16x32_bf16 v[180:183], v[168:171], v[160:163], v[180:183]
	v_mfma_f32_16x16x32_bf16 v[184:187], v[172:175], v[160:163], v[184:187]
	global_load_dwordx4 v[144:147], v8, s[16:17] offset:1792
	global_load_dwordx4 v[148:151], v9, s[18:19] offset:1792
	global_load_dwordx4 v[152:155], v10, s[18:19] offset:1792
	global_load_dwordx4 v[156:159], v11, s[18:19] offset:1792
	global_load_dwordx4 v[160:163], v8, s[16:17] offset:1856
	global_load_dwordx4 v[164:167], v9, s[18:19] offset:1856
	global_load_dwordx4 v[168:171], v10, s[18:19] offset:1856
	global_load_dwordx4 v[172:175], v11, s[18:19] offset:1856
	s_waitcnt vmcnt(32)
	v_mfma_f32_16x16x32_bf16 v[176:179], v[20:23], v[16:19], v[176:179]
	v_mfma_f32_16x16x32_bf16 v[180:183], v[24:27], v[16:19], v[180:183]
	v_mfma_f32_16x16x32_bf16 v[184:187], v[28:31], v[16:19], v[184:187]
	v_mfma_f32_16x16x32_bf16 v[176:179], v[36:39], v[32:35], v[176:179]
	v_mfma_f32_16x16x32_bf16 v[180:183], v[40:43], v[32:35], v[180:183]
	v_mfma_f32_16x16x32_bf16 v[184:187], v[44:47], v[32:35], v[184:187]
	global_load_dwordx4 v[16:19], v8, s[16:17] offset:1920
	global_load_dwordx4 v[20:23], v9, s[18:19] offset:1920
	global_load_dwordx4 v[24:27], v10, s[18:19] offset:1920
	global_load_dwordx4 v[28:31], v11, s[18:19] offset:1920
	global_load_dwordx4 v[32:35], v8, s[16:17] offset:1984
	global_load_dwordx4 v[36:39], v9, s[18:19] offset:1984
	global_load_dwordx4 v[40:43], v10, s[18:19] offset:1984
	global_load_dwordx4 v[44:47], v11, s[18:19] offset:1984
	s_waitcnt vmcnt(32)
	v_mfma_f32_16x16x32_bf16 v[176:179], v[52:55], v[48:51], v[176:179]
	v_mfma_f32_16x16x32_bf16 v[180:183], v[56:59], v[48:51], v[180:183]
	v_mfma_f32_16x16x32_bf16 v[184:187], v[60:63], v[48:51], v[184:187]
	v_mfma_f32_16x16x32_bf16 v[176:179], v[68:71], v[64:67], v[176:179]
	v_mfma_f32_16x16x32_bf16 v[180:183], v[72:75], v[64:67], v[180:183]
	v_mfma_f32_16x16x32_bf16 v[184:187], v[76:79], v[64:67], v[184:187]
	global_load_dwordx4 v[48:51], v8, s[16:17] offset:2048
	global_load_dwordx4 v[52:55], v9, s[18:19] offset:2048
	global_load_dwordx4 v[56:59], v10, s[18:19] offset:2048
	global_load_dwordx4 v[60:63], v11, s[18:19] offset:2048
	global_load_dwordx4 v[64:67], v8, s[16:17] offset:2112
	global_load_dwordx4 v[68:71], v9, s[18:19] offset:2112
	global_load_dwordx4 v[72:75], v10, s[18:19] offset:2112
	global_load_dwordx4 v[76:79], v11, s[18:19] offset:2112
	s_waitcnt vmcnt(32)
	v_mfma_f32_16x16x32_bf16 v[176:179], v[84:87], v[80:83], v[176:179]
	v_mfma_f32_16x16x32_bf16 v[180:183], v[88:91], v[80:83], v[180:183]
	v_mfma_f32_16x16x32_bf16 v[184:187], v[92:95], v[80:83], v[184:187]
	v_mfma_f32_16x16x32_bf16 v[176:179], v[100:103], v[96:99], v[176:179]
	v_mfma_f32_16x16x32_bf16 v[180:183], v[104:107], v[96:99], v[180:183]
	v_mfma_f32_16x16x32_bf16 v[184:187], v[108:111], v[96:99], v[184:187]
	global_load_dwordx4 v[80:83], v8, s[16:17] offset:2176
	global_load_dwordx4 v[84:87], v9, s[18:19] offset:2176
	global_load_dwordx4 v[88:91], v10, s[18:19] offset:2176
	global_load_dwordx4 v[92:95], v11, s[18:19] offset:2176
	global_load_dwordx4 v[96:99], v8, s[16:17] offset:2240
	global_load_dwordx4 v[100:103], v9, s[18:19] offset:2240
	global_load_dwordx4 v[104:107], v10, s[18:19] offset:2240
	global_load_dwordx4 v[108:111], v11, s[18:19] offset:2240
	s_waitcnt vmcnt(32)
	v_mfma_f32_16x16x32_bf16 v[176:179], v[116:119], v[112:115], v[176:179]
	v_mfma_f32_16x16x32_bf16 v[180:183], v[120:123], v[112:115], v[180:183]
	v_mfma_f32_16x16x32_bf16 v[184:187], v[124:127], v[112:115], v[184:187]
	v_mfma_f32_16x16x32_bf16 v[176:179], v[132:135], v[128:131], v[176:179]
	v_mfma_f32_16x16x32_bf16 v[180:183], v[136:139], v[128:131], v[180:183]
	v_mfma_f32_16x16x32_bf16 v[184:187], v[140:143], v[128:131], v[184:187]
	global_load_dwordx4 v[112:115], v8, s[16:17] offset:2304
	global_load_dwordx4 v[116:119], v9, s[18:19] offset:2304
	global_load_dwordx4 v[120:123], v10, s[18:19] offset:2304
	global_load_dwordx4 v[124:127], v11, s[18:19] offset:2304
	global_load_dwordx4 v[128:131], v8, s[16:17] offset:2368
	global_load_dwordx4 v[132:135], v9, s[18:19] offset:2368
	global_load_dwordx4 v[136:139], v10, s[18:19] offset:2368
	global_load_dwordx4 v[140:143], v11, s[18:19] offset:2368
	s_waitcnt vmcnt(32)
	v_mfma_f32_16x16x32_bf16 v[176:179], v[148:151], v[144:147], v[176:179]
	v_mfma_f32_16x16x32_bf16 v[180:183], v[152:155], v[144:147], v[180:183]
	v_mfma_f32_16x16x32_bf16 v[184:187], v[156:159], v[144:147], v[184:187]
	v_mfma_f32_16x16x32_bf16 v[176:179], v[164:167], v[160:163], v[176:179]
	v_mfma_f32_16x16x32_bf16 v[180:183], v[168:171], v[160:163], v[180:183]
	v_mfma_f32_16x16x32_bf16 v[184:187], v[172:175], v[160:163], v[184:187]
	global_load_dwordx4 v[144:147], v8, s[16:17] offset:2432
	global_load_dwordx4 v[148:151], v9, s[18:19] offset:2432
	global_load_dwordx4 v[152:155], v10, s[18:19] offset:2432
	global_load_dwordx4 v[156:159], v11, s[18:19] offset:2432
	global_load_dwordx4 v[160:163], v8, s[16:17] offset:2496
	global_load_dwordx4 v[164:167], v9, s[18:19] offset:2496
	global_load_dwordx4 v[168:171], v10, s[18:19] offset:2496
	global_load_dwordx4 v[172:175], v11, s[18:19] offset:2496
	s_waitcnt vmcnt(32)
	v_mfma_f32_16x16x32_bf16 v[176:179], v[20:23], v[16:19], v[176:179]
	v_mfma_f32_16x16x32_bf16 v[180:183], v[24:27], v[16:19], v[180:183]
	v_mfma_f32_16x16x32_bf16 v[184:187], v[28:31], v[16:19], v[184:187]
	v_mfma_f32_16x16x32_bf16 v[176:179], v[36:39], v[32:35], v[176:179]
	v_mfma_f32_16x16x32_bf16 v[180:183], v[40:43], v[32:35], v[180:183]
	v_mfma_f32_16x16x32_bf16 v[184:187], v[44:47], v[32:35], v[184:187]
	global_load_dwordx4 v[16:19], v8, s[16:17] offset:2560
	global_load_dwordx4 v[20:23], v9, s[18:19] offset:2560
	global_load_dwordx4 v[24:27], v10, s[18:19] offset:2560
	global_load_dwordx4 v[28:31], v11, s[18:19] offset:2560
	global_load_dwordx4 v[32:35], v8, s[16:17] offset:2624
	global_load_dwordx4 v[36:39], v9, s[18:19] offset:2624
	global_load_dwordx4 v[40:43], v10, s[18:19] offset:2624
	global_load_dwordx4 v[44:47], v11, s[18:19] offset:2624
	s_waitcnt vmcnt(32)
	v_mfma_f32_16x16x32_bf16 v[176:179], v[52:55], v[48:51], v[176:179]
	v_mfma_f32_16x16x32_bf16 v[180:183], v[56:59], v[48:51], v[180:183]
	v_mfma_f32_16x16x32_bf16 v[184:187], v[60:63], v[48:51], v[184:187]
	v_mfma_f32_16x16x32_bf16 v[176:179], v[68:71], v[64:67], v[176:179]
	v_mfma_f32_16x16x32_bf16 v[180:183], v[72:75], v[64:67], v[180:183]
	v_mfma_f32_16x16x32_bf16 v[184:187], v[76:79], v[64:67], v[184:187]
	global_load_dwordx4 v[48:51], v8, s[16:17] offset:2688
	global_load_dwordx4 v[52:55], v9, s[18:19] offset:2688
	global_load_dwordx4 v[56:59], v10, s[18:19] offset:2688
	global_load_dwordx4 v[60:63], v11, s[18:19] offset:2688
	global_load_dwordx4 v[64:67], v8, s[16:17] offset:2752
	global_load_dwordx4 v[68:71], v9, s[18:19] offset:2752
	global_load_dwordx4 v[72:75], v10, s[18:19] offset:2752
	global_load_dwordx4 v[76:79], v11, s[18:19] offset:2752
	s_waitcnt vmcnt(32)
	v_mfma_f32_16x16x32_bf16 v[176:179], v[84:87], v[80:83], v[176:179]
	v_mfma_f32_16x16x32_bf16 v[180:183], v[88:91], v[80:83], v[180:183]
	v_mfma_f32_16x16x32_bf16 v[184:187], v[92:95], v[80:83], v[184:187]
	v_mfma_f32_16x16x32_bf16 v[176:179], v[100:103], v[96:99], v[176:179]
	v_mfma_f32_16x16x32_bf16 v[180:183], v[104:107], v[96:99], v[180:183]
	v_mfma_f32_16x16x32_bf16 v[184:187], v[108:111], v[96:99], v[184:187]
	global_load_dwordx4 v[80:83], v8, s[16:17] offset:2816
	global_load_dwordx4 v[84:87], v9, s[18:19] offset:2816
	global_load_dwordx4 v[88:91], v10, s[18:19] offset:2816
	global_load_dwordx4 v[92:95], v11, s[18:19] offset:2816
	global_load_dwordx4 v[96:99], v8, s[16:17] offset:2880
	global_load_dwordx4 v[100:103], v9, s[18:19] offset:2880
	global_load_dwordx4 v[104:107], v10, s[18:19] offset:2880
	global_load_dwordx4 v[108:111], v11, s[18:19] offset:2880
	s_waitcnt vmcnt(32)
	v_mfma_f32_16x16x32_bf16 v[176:179], v[116:119], v[112:115], v[176:179]
	v_mfma_f32_16x16x32_bf16 v[180:183], v[120:123], v[112:115], v[180:183]
	v_mfma_f32_16x16x32_bf16 v[184:187], v[124:127], v[112:115], v[184:187]
	v_mfma_f32_16x16x32_bf16 v[176:179], v[132:135], v[128:131], v[176:179]
	v_mfma_f32_16x16x32_bf16 v[180:183], v[136:139], v[128:131], v[180:183]
	v_mfma_f32_16x16x32_bf16 v[184:187], v[140:143], v[128:131], v[184:187]
	global_load_dwordx4 v[112:115], v8, s[16:17] offset:2944
	global_load_dwordx4 v[116:119], v9, s[18:19] offset:2944
	global_load_dwordx4 v[120:123], v10, s[18:19] offset:2944
	global_load_dwordx4 v[124:127], v11, s[18:19] offset:2944
	global_load_dwordx4 v[128:131], v8, s[16:17] offset:3008
	global_load_dwordx4 v[132:135], v9, s[18:19] offset:3008
	global_load_dwordx4 v[136:139], v10, s[18:19] offset:3008
	global_load_dwordx4 v[140:143], v11, s[18:19] offset:3008
	s_waitcnt vmcnt(32)
	v_mfma_f32_16x16x32_bf16 v[176:179], v[148:151], v[144:147], v[176:179]
	v_mfma_f32_16x16x32_bf16 v[180:183], v[152:155], v[144:147], v[180:183]
	v_mfma_f32_16x16x32_bf16 v[184:187], v[156:159], v[144:147], v[184:187]
	v_mfma_f32_16x16x32_bf16 v[176:179], v[164:167], v[160:163], v[176:179]
	v_mfma_f32_16x16x32_bf16 v[180:183], v[168:171], v[160:163], v[180:183]
	v_mfma_f32_16x16x32_bf16 v[184:187], v[172:175], v[160:163], v[184:187]
	global_load_dwordx4 v[144:147], v8, s[16:17] offset:3072
	global_load_dwordx4 v[148:151], v9, s[18:19] offset:3072
	global_load_dwordx4 v[152:155], v10, s[18:19] offset:3072
	global_load_dwordx4 v[156:159], v11, s[18:19] offset:3072
	global_load_dwordx4 v[160:163], v8, s[16:17] offset:3136
	global_load_dwordx4 v[164:167], v9, s[18:19] offset:3136
	global_load_dwordx4 v[168:171], v10, s[18:19] offset:3136
	global_load_dwordx4 v[172:175], v11, s[18:19] offset:3136
	s_waitcnt vmcnt(32)
	v_mfma_f32_16x16x32_bf16 v[176:179], v[20:23], v[16:19], v[176:179]
	v_mfma_f32_16x16x32_bf16 v[180:183], v[24:27], v[16:19], v[180:183]
	v_mfma_f32_16x16x32_bf16 v[184:187], v[28:31], v[16:19], v[184:187]
	v_mfma_f32_16x16x32_bf16 v[176:179], v[36:39], v[32:35], v[176:179]
	v_mfma_f32_16x16x32_bf16 v[180:183], v[40:43], v[32:35], v[180:183]
	v_mfma_f32_16x16x32_bf16 v[184:187], v[44:47], v[32:35], v[184:187]
	global_load_dwordx4 v[16:19], v8, s[16:17] offset:3200
	global_load_dwordx4 v[20:23], v9, s[18:19] offset:3200
	global_load_dwordx4 v[24:27], v10, s[18:19] offset:3200
	global_load_dwordx4 v[28:31], v11, s[18:19] offset:3200
	global_load_dwordx4 v[32:35], v8, s[16:17] offset:3264
	global_load_dwordx4 v[36:39], v9, s[18:19] offset:3264
	global_load_dwordx4 v[40:43], v10, s[18:19] offset:3264
	global_load_dwordx4 v[44:47], v11, s[18:19] offset:3264
	s_waitcnt vmcnt(32)
	v_mfma_f32_16x16x32_bf16 v[176:179], v[52:55], v[48:51], v[176:179]
	v_mfma_f32_16x16x32_bf16 v[180:183], v[56:59], v[48:51], v[180:183]
	v_mfma_f32_16x16x32_bf16 v[184:187], v[60:63], v[48:51], v[184:187]
	v_mfma_f32_16x16x32_bf16 v[176:179], v[68:71], v[64:67], v[176:179]
	v_mfma_f32_16x16x32_bf16 v[180:183], v[72:75], v[64:67], v[180:183]
	v_mfma_f32_16x16x32_bf16 v[184:187], v[76:79], v[64:67], v[184:187]
	global_load_dwordx4 v[48:51], v8, s[16:17] offset:3328
	global_load_dwordx4 v[52:55], v9, s[18:19] offset:3328
	global_load_dwordx4 v[56:59], v10, s[18:19] offset:3328
	global_load_dwordx4 v[60:63], v11, s[18:19] offset:3328
	global_load_dwordx4 v[64:67], v8, s[16:17] offset:3392
	global_load_dwordx4 v[68:71], v9, s[18:19] offset:3392
	global_load_dwordx4 v[72:75], v10, s[18:19] offset:3392
	global_load_dwordx4 v[76:79], v11, s[18:19] offset:3392
	s_waitcnt vmcnt(32)
	v_mfma_f32_16x16x32_bf16 v[176:179], v[84:87], v[80:83], v[176:179]
	v_mfma_f32_16x16x32_bf16 v[180:183], v[88:91], v[80:83], v[180:183]
	v_mfma_f32_16x16x32_bf16 v[184:187], v[92:95], v[80:83], v[184:187]
	v_mfma_f32_16x16x32_bf16 v[176:179], v[100:103], v[96:99], v[176:179]
	v_mfma_f32_16x16x32_bf16 v[180:183], v[104:107], v[96:99], v[180:183]
	v_mfma_f32_16x16x32_bf16 v[184:187], v[108:111], v[96:99], v[184:187]
	global_load_dwordx4 v[80:83], v8, s[16:17] offset:3456
	global_load_dwordx4 v[84:87], v9, s[18:19] offset:3456
	global_load_dwordx4 v[88:91], v10, s[18:19] offset:3456
	global_load_dwordx4 v[92:95], v11, s[18:19] offset:3456
	global_load_dwordx4 v[96:99], v8, s[16:17] offset:3520
	global_load_dwordx4 v[100:103], v9, s[18:19] offset:3520
	global_load_dwordx4 v[104:107], v10, s[18:19] offset:3520
	global_load_dwordx4 v[108:111], v11, s[18:19] offset:3520
	s_waitcnt vmcnt(32)
	v_mfma_f32_16x16x32_bf16 v[176:179], v[116:119], v[112:115], v[176:179]
	v_mfma_f32_16x16x32_bf16 v[180:183], v[120:123], v[112:115], v[180:183]
	v_mfma_f32_16x16x32_bf16 v[184:187], v[124:127], v[112:115], v[184:187]
	v_mfma_f32_16x16x32_bf16 v[176:179], v[132:135], v[128:131], v[176:179]
	v_mfma_f32_16x16x32_bf16 v[180:183], v[136:139], v[128:131], v[180:183]
	v_mfma_f32_16x16x32_bf16 v[184:187], v[140:143], v[128:131], v[184:187]
	global_load_dwordx4 v[112:115], v8, s[16:17] offset:3584
	global_load_dwordx4 v[116:119], v9, s[18:19] offset:3584
	global_load_dwordx4 v[120:123], v10, s[18:19] offset:3584
	global_load_dwordx4 v[124:127], v11, s[18:19] offset:3584
	global_load_dwordx4 v[128:131], v8, s[16:17] offset:3648
	global_load_dwordx4 v[132:135], v9, s[18:19] offset:3648
	global_load_dwordx4 v[136:139], v10, s[18:19] offset:3648
	global_load_dwordx4 v[140:143], v11, s[18:19] offset:3648
	s_waitcnt vmcnt(32)
	v_mfma_f32_16x16x32_bf16 v[176:179], v[148:151], v[144:147], v[176:179]
	v_mfma_f32_16x16x32_bf16 v[180:183], v[152:155], v[144:147], v[180:183]
	v_mfma_f32_16x16x32_bf16 v[184:187], v[156:159], v[144:147], v[184:187]
	v_mfma_f32_16x16x32_bf16 v[176:179], v[164:167], v[160:163], v[176:179]
	v_mfma_f32_16x16x32_bf16 v[180:183], v[168:171], v[160:163], v[180:183]
	v_mfma_f32_16x16x32_bf16 v[184:187], v[172:175], v[160:163], v[184:187]
	global_load_dwordx4 v[144:147], v8, s[16:17] offset:3712
	global_load_dwordx4 v[148:151], v9, s[18:19] offset:3712
	global_load_dwordx4 v[152:155], v10, s[18:19] offset:3712
	global_load_dwordx4 v[156:159], v11, s[18:19] offset:3712
	global_load_dwordx4 v[160:163], v8, s[16:17] offset:3776
	global_load_dwordx4 v[164:167], v9, s[18:19] offset:3776
	global_load_dwordx4 v[168:171], v10, s[18:19] offset:3776
	global_load_dwordx4 v[172:175], v11, s[18:19] offset:3776
	s_waitcnt vmcnt(32)
; template <int EPI>
; DI void gemm_unit(const GemmP& g, int pm, int pn) {
;     ...
;             const int col = colb + bj * 128 + n * 16;
;             f32x4 v = acc[ai][bj][m][n];
;             if (EPI == EPI_BF16) {
;               if (col >= g.aux_n0) {
;                 const int c2 = col - g.aux_n0;
;                 if (c2 < g.aux_cnt) *(f32x4*)(g.aux + (size_t)row * 16 + c2) = v * g.aux_scale;
;               } else {
;                 if (g.colscale) v = v * *(const f32x4*)(g.colscale + col);
;                 uint2 o; o.x = pk2(v[0], v[1]); o.y = pk2(v[2], v[3]);
;                 *(uint2*)(g.Cb + (size_t)row * g.ldc + col) = o;
	v_mfma_f32_16x16x32_bf16 v[176:179], v[20:23], v[16:19], v[176:179]
	v_mfma_f32_16x16x32_bf16 v[180:183], v[24:27], v[16:19], v[180:183]
	v_mfma_f32_16x16x32_bf16 v[184:187], v[28:31], v[16:19], v[184:187]
	v_mfma_f32_16x16x32_bf16 v[176:179], v[36:39], v[32:35], v[176:179]
	v_mfma_f32_16x16x32_bf16 v[180:183], v[40:43], v[32:35], v[180:183]
	v_mfma_f32_16x16x32_bf16 v[184:187], v[44:47], v[32:35], v[184:187]
	global_load_dwordx4 v[16:19], v8, s[16:17] offset:3840
	global_load_dwordx4 v[20:23], v9, s[18:19] offset:3840
	global_load_dwordx4 v[24:27], v10, s[18:19] offset:3840
	global_load_dwordx4 v[28:31], v11, s[18:19] offset:3840
	global_load_dwordx4 v[32:35], v8, s[16:17] offset:3904
	global_load_dwordx4 v[36:39], v9, s[18:19] offset:3904
	global_load_dwordx4 v[40:43], v10, s[18:19] offset:3904
	global_load_dwordx4 v[44:47], v11, s[18:19] offset:3904
	s_waitcnt vmcnt(32)
	v_mfma_f32_16x16x32_bf16 v[176:179], v[52:55], v[48:51], v[176:179]
	v_mfma_f32_16x16x32_bf16 v[180:183], v[56:59], v[48:51], v[180:183]
	v_mfma_f32_16x16x32_bf16 v[184:187], v[60:63], v[48:51], v[184:187]
	v_mfma_f32_16x16x32_bf16 v[176:179], v[68:71], v[64:67], v[176:179]
	v_mfma_f32_16x16x32_bf16 v[180:183], v[72:75], v[64:67], v[180:183]
	v_mfma_f32_16x16x32_bf16 v[184:187], v[76:79], v[64:67], v[184:187]
	global_load_dwordx4 v[48:51], v8, s[16:17] offset:3968
	global_load_dwordx4 v[52:55], v9, s[18:19] offset:3968
	global_load_dwordx4 v[56:59], v10, s[18:19] offset:3968
	global_load_dwordx4 v[60:63], v11, s[18:19] offset:3968
	global_load_dwordx4 v[64:67], v8, s[16:17] offset:4032
	global_load_dwordx4 v[68:71], v9, s[18:19] offset:4032
	global_load_dwordx4 v[72:75], v10, s[18:19] offset:4032
	global_load_dwordx4 v[76:79], v11, s[18:19] offset:4032
	s_waitcnt vmcnt(32)
	v_mfma_f32_16x16x32_bf16 v[176:179], v[84:87], v[80:83], v[176:179]
	v_mfma_f32_16x16x32_bf16 v[180:183], v[88:91], v[80:83], v[180:183]
	v_mfma_f32_16x16x32_bf16 v[184:187], v[92:95], v[80:83], v[184:187]
	v_mfma_f32_16x16x32_bf16 v[176:179], v[100:103], v[96:99], v[176:179]
	v_mfma_f32_16x16x32_bf16 v[180:183], v[104:107], v[96:99], v[180:183]
	v_mfma_f32_16x16x32_bf16 v[184:187], v[108:111], v[96:99], v[184:187]
	s_waitcnt vmcnt(24)
	v_mfma_f32_16x16x32_bf16 v[176:179], v[116:119], v[112:115], v[176:179]
	v_mfma_f32_16x16x32_bf16 v[180:183], v[120:123], v[112:115], v[180:183]
	v_mfma_f32_16x16x32_bf16 v[184:187], v[124:127], v[112:115], v[184:187]
	v_mfma_f32_16x16x32_bf16 v[176:179], v[132:135], v[128:131], v[176:179]
	v_mfma_f32_16x16x32_bf16 v[180:183], v[136:139], v[128:131], v[180:183]
	v_mfma_f32_16x16x32_bf16 v[184:187], v[140:143], v[128:131], v[184:187]
	s_waitcnt vmcnt(16)
	v_mfma_f32_16x16x32_bf16 v[176:179], v[148:151], v[144:147], v[176:179]
	v_mfma_f32_16x16x32_bf16 v[180:183], v[152:155], v[144:147], v[180:183]
	v_mfma_f32_16x16x32_bf16 v[184:187], v[156:159], v[144:147], v[184:187]
	v_mfma_f32_16x16x32_bf16 v[176:179], v[164:167], v[160:163], v[176:179]
	v_mfma_f32_16x16x32_bf16 v[180:183], v[168:171], v[160:163], v[180:183]
	v_mfma_f32_16x16x32_bf16 v[184:187], v[172:175], v[160:163], v[184:187]
	s_waitcnt vmcnt(8)
	v_mfma_f32_16x16x32_bf16 v[176:179], v[20:23], v[16:19], v[176:179]
	v_mfma_f32_16x16x32_bf16 v[180:183], v[24:27], v[16:19], v[180:183]
	v_mfma_f32_16x16x32_bf16 v[184:187], v[28:31], v[16:19], v[184:187]
	v_mfma_f32_16x16x32_bf16 v[176:179], v[36:39], v[32:35], v[176:179]
	v_mfma_f32_16x16x32_bf16 v[180:183], v[40:43], v[32:35], v[180:183]
	v_mfma_f32_16x16x32_bf16 v[184:187], v[44:47], v[32:35], v[184:187]
	s_waitcnt vmcnt(0)
	v_mfma_f32_16x16x32_bf16 v[176:179], v[52:55], v[48:51], v[176:179]
	v_mfma_f32_16x16x32_bf16 v[180:183], v[56:59], v[48:51], v[180:183]
	v_mfma_f32_16x16x32_bf16 v[184:187], v[60:63], v[48:51], v[184:187]
	v_mfma_f32_16x16x32_bf16 v[176:179], v[68:71], v[64:67], v[176:179]
	v_mfma_f32_16x16x32_bf16 v[180:183], v[72:75], v[64:67], v[180:183]
	v_mfma_f32_16x16x32_bf16 v[184:187], v[76:79], v[64:67], v[184:187]
	s_nop 7
	s_nop 7
	s_add_u32 s18, s90, 0x26b00000
	s_addc_u32 s19, s91, 0
	v_mul_u32_u24_e32 v12, 0x2a00, v5
	v_lshl_add_u32 v12, v4, 3, v12
	v_add_u32_e32 v12, 0x2000, v12
	v_cvt_pk_bf16_f32 v14, v176, v177
	v_cvt_pk_bf16_f32 v15, v178, v179
	s_cmp_eq_u32 s15, 0
	s_cbranch_scc0 .Lki_hi
	v_cvt_pk_bf16_f32 v16, v180, v181
	v_cvt_pk_bf16_f32 v17, v182, v183
	v_cvt_pk_bf16_f32 v18, v184, v185
	v_cvt_pk_bf16_f32 v19, v186, v187
	global_store_dwordx2 v12, v[14:15], s[18:19]
	global_store_dwordx2 v12, v[16:17], s[18:19] offset:32
	global_store_dwordx2 v12, v[18:19], s[18:19] offset:64
	s_branch .Lki_done
.Lki_hi:
	v_mul_f32_e32 v180, 0x3e800000, v180
	v_mul_f32_e32 v181, 0x3e800000, v181
	v_mul_f32_e32 v182, 0x3e800000, v182
	v_mul_f32_e32 v183, 0x3e800000, v183
	v_lshl_or_b32 v7, v5, 6, v6
	global_store_dwordx2 v12, v[14:15], s[18:19] offset:96
	global_store_dwordx4 v7, v[180:183], s[20:21]
.Lki_done:
	s_mov_b32 s8, 16
.Lki_skip:
	s_mul_hi_i32 s53, s58, 0x1100000
	s_mul_i32 s52, s58, 0x1100000
	s_mov_b32 s16, 0x3e800000
	s_movk_i32 s39, 0x1040
	s_mov_b32 s44, 16
	s_mov_b64 s[6:7], 0x2200000
	s_branch .LBB0_986
